# v80 + diff-attention loops: LDS-DMA source addresses as scalar base + 32-bit lane offset (L0 all six per iteration, L1 the four V DMAs) instead of 64-bit VALU adds
# speedup vs baseline: 1.0028x; 1.0028x over previous
.LBB0_906:
	s_add_u32 s100, s4, s12
	s_addc_u32 s101, s5, s13
	s_mov_b32 m0, s35
	s_nop 0
	global_load_lds_dwordx4 v172, s[100:101]
	s_mov_b32 m0, s86
	s_nop 0
	global_load_lds_dwordx4 v174, s[100:101]
	ds_read_b128 v[66:69], v188 offset:40960
	ds_read_b128 v[70:73], v188 offset:45056
	ds_read_b128 v[82:85], v189 offset:40960
	ds_read_b128 v[86:89], v189 offset:45056
	ds_read_b128 v[90:93], v190 offset:40960
	ds_read_b128 v[176:179], v190 offset:45056
	ds_read_b128 v[192:195], v191 offset:40960
	ds_read_b128 v[196:199], v191 offset:45056
	v_add_f32_e32 v216, v216, v1
	s_waitcnt lgkmcnt(0)
	v_mfma_f32_32x32x16_bf16 v[112:127], v[66:69], v[128:131], 0
	v_mfma_f32_32x32x16_bf16 v[66:81], v[70:73], v[128:131], 0
	v_mfma_f32_32x32x16_bf16 v[66:81], v[86:89], v[132:135], v[66:81]
	v_mfma_f32_32x32x16_bf16 v[112:127], v[82:85], v[132:135], v[112:127]
	v_add_f32_e32 v86, v238, v239
	v_add_f32_e32 v87, v222, v223
	v_mfma_f32_32x32x16_bf16 v[66:81], v[176:179], v[136:139], v[66:81]
	v_add_f32_e32 v86, v86, v240
	v_add_f32_e32 v87, v87, v224
	v_cvt_pk_bf16_f32 v94, v238, v239
	v_add_f32_e32 v86, v86, v241
	v_add_f32_e32 v87, v87, v225
	v_cvt_pk_bf16_f32 v95, v240, v241
	v_add_f32_e32 v86, v86, v244
	v_add_f32_e32 v87, v87, v226
	v_cvt_pk_bf16_f32 v96, v244, v245
	v_add_f32_e32 v86, v86, v245
	v_add_f32_e32 v87, v87, v227
	v_cvt_pk_bf16_f32 v97, v246, v247
	v_add_f32_e32 v86, v86, v246
	v_add_f32_e32 v87, v87, v228
	s_nop 0
	v_add_f32_e32 v86, v86, v247
	v_add_f32_e32 v87, v87, v229
	v_add_f32_e32 v86, v86, v248
	v_add_f32_e32 v87, v87, v230
	v_mfma_f32_32x32x16_bf16 v[112:127], v[90:93], v[136:139], v[112:127]
	v_add_f32_e32 v86, v86, v249
	v_add_f32_e32 v87, v87, v231
	v_add_f32_e32 v86, v86, v250
	v_add_f32_e32 v87, v87, v232
	v_add_f32_e32 v86, v86, v251
	v_add_f32_e32 v87, v87, v233
	v_add_f32_e32 v86, v86, v252
	v_add_f32_e32 v87, v87, v234
	v_add_f32_e32 v86, v86, v253
	v_add_f32_e32 v87, v87, v235
	v_add_f32_e32 v86, v86, v254
	v_add_f32_e32 v87, v87, v236
	v_add_f32_e32 v86, v86, v255
	v_add_f32_e32 v87, v87, v237
	v_add_f32_e32 v86, v86, v87
	v_add_f32_e32 v216, v216, v86
	v_mfma_f32_32x32x16_bf16 v[66:81], v[196:199], v[140:143], v[66:81]
	v_cvt_pk_bf16_f32 v98, v248, v249
	v_cvt_pk_bf16_f32 v99, v250, v251
	v_cvt_pk_bf16_f32 v100, v252, v253
	v_cvt_pk_bf16_f32 v101, v254, v255
	v_cvt_pk_bf16_f32 v102, v222, v223
	v_cvt_pk_bf16_f32 v103, v224, v225
	v_cvt_pk_bf16_f32 v104, v226, v227
	v_cvt_pk_bf16_f32 v105, v228, v229
	v_cvt_pk_bf16_f32 v106, v230, v231
	v_cvt_pk_bf16_f32 v107, v232, v233
	v_cvt_pk_bf16_f32 v108, v234, v235
	v_cvt_pk_bf16_f32 v109, v236, v237
	v_mfma_f32_32x32x16_bf16 v[112:127], v[192:195], v[140:143], v[112:127]
	ds_read_b64_tr_b16 v[82:83], v184 offset:0
	ds_read_b64_tr_b16 v[84:85], v184 offset:0x800
	ds_read_b64_tr_b16 v[86:87], v184 offset:0x1000
	ds_read_b64_tr_b16 v[88:89], v184 offset:0x1800
	ds_read_b64_tr_b16 v[90:91], v184 offset:0x2000
	ds_read_b64_tr_b16 v[92:93], v184 offset:0x2800
	ds_read_b64_tr_b16 v[176:177], v184 offset:0x3000
	ds_read_b64_tr_b16 v[178:179], v184 offset:0x3800
	ds_read_b64_tr_b16 v[192:193], v184 offset:0x200
	ds_read_b64_tr_b16 v[194:195], v184 offset:0xa00
	ds_read_b64_tr_b16 v[196:197], v184 offset:0x1200
	ds_read_b64_tr_b16 v[198:199], v184 offset:0x1a00
	ds_read_b64_tr_b16 v[200:201], v184 offset:0x2200
	ds_read_b64_tr_b16 v[202:203], v184 offset:0x2a00
	ds_read_b64_tr_b16 v[204:205], v184 offset:0x3200
	ds_read_b64_tr_b16 v[206:207], v184 offset:0x3a00
	s_waitcnt lgkmcnt(8)
	s_nop 0
	v_mfma_f32_32x32x16_bf16 v[2:17], v[94:97], v[82:85], v[2:17]
	v_exp_f32_e32 v222, v66
	s_nop 3
	v_exp_f32_e32 v1, v113
	v_exp_f32_e32 v82, v114
	v_exp_f32_e32 v83, v115
	v_mfma_f32_32x32x16_bf16 v[2:17], v[98:101], v[86:89], v[2:17]
	v_exp_f32_e32 v223, v67
	v_exp_f32_e32 v88, v112
	v_mfma_f32_32x32x16_bf16 v[2:17], v[102:105], v[90:93], v[2:17]
	v_exp_f32_e32 v224, v68
	v_mfma_f32_32x32x16_bf16 v[2:17], v[106:109], v[176:179], v[2:17]
	v_exp_f32_e32 v225, v69
	ds_read_b64_tr_b16 v[90:91], v184 offset:0x400
	ds_read_b64_tr_b16 v[92:93], v184 offset:0xc00
	ds_read_b64_tr_b16 v[110:111], v184 offset:0x1400
	ds_read_b64_tr_b16 v[112:113], v184 offset:0x1c00
	ds_read_b64_tr_b16 v[176:177], v184 offset:0x2400
	ds_read_b64_tr_b16 v[178:179], v184 offset:0x2c00
	ds_read_b64_tr_b16 v[208:209], v184 offset:0x3400
	ds_read_b64_tr_b16 v[210:211], v184 offset:0x3c00
	s_waitcnt lgkmcnt(8)
	v_mfma_f32_32x32x16_bf16 v[18:33], v[94:97], v[192:195], v[18:33]
	v_exp_f32_e32 v226, v70
	v_exp_f32_e32 v84, v116
	v_exp_f32_e32 v85, v117
	v_exp_f32_e32 v86, v118
	v_exp_f32_e32 v87, v119
	v_mfma_f32_32x32x16_bf16 v[18:33], v[98:101], v[196:199], v[18:33]
	v_exp_f32_e32 v227, v71
	v_mfma_f32_32x32x16_bf16 v[18:33], v[102:105], v[200:203], v[18:33]
	v_exp_f32_e32 v228, v72
	v_mfma_f32_32x32x16_bf16 v[18:33], v[106:109], v[204:207], v[18:33]
	v_exp_f32_e32 v229, v73
	ds_read_b64_tr_b16 v[114:115], v184 offset:0x600
	ds_read_b64_tr_b16 v[116:117], v184 offset:0xe00
	ds_read_b64_tr_b16 v[192:193], v184 offset:0x1600
	ds_read_b64_tr_b16 v[194:195], v184 offset:0x1e00
	ds_read_b64_tr_b16 v[196:197], v184 offset:0x2600
	ds_read_b64_tr_b16 v[198:199], v184 offset:0x2e00
	ds_read_b64_tr_b16 v[200:201], v184 offset:0x3600
	ds_read_b64_tr_b16 v[202:203], v184 offset:0x3e00
	s_waitcnt lgkmcnt(8)
	v_mfma_f32_32x32x16_bf16 v[34:49], v[94:97], v[90:93], v[34:49]
	v_exp_f32_e32 v230, v74
	v_exp_f32_e32 v90, v120
	v_exp_f32_e32 v89, v121
	v_exp_f32_e32 v92, v122
	v_exp_f32_e32 v91, v123
	v_mfma_f32_32x32x16_bf16 v[34:49], v[98:101], v[110:113], v[34:49]
	v_exp_f32_e32 v231, v75
	v_mfma_f32_32x32x16_bf16 v[34:49], v[102:105], v[176:179], v[34:49]
	v_exp_f32_e32 v232, v76
	v_mfma_f32_32x32x16_bf16 v[34:49], v[106:109], v[208:211], v[34:49]
	v_exp_f32_e32 v233, v77
	s_waitcnt lgkmcnt(0)
	v_mfma_f32_32x32x16_bf16 v[50:65], v[94:97], v[114:117], v[50:65]
	v_exp_f32_e32 v234, v78
	v_exp_f32_e32 v94, v124
	v_exp_f32_e32 v93, v125
	v_exp_f32_e32 v95, v126
	v_exp_f32_e32 v151, v127
	v_mfma_f32_32x32x16_bf16 v[50:65], v[98:101], v[192:195], v[50:65]
	v_exp_f32_e32 v235, v79
	v_mfma_f32_32x32x16_bf16 v[50:65], v[102:105], v[196:199], v[50:65]
	v_exp_f32_e32 v236, v80
	v_mfma_f32_32x32x16_bf16 v[50:65], v[106:109], v[200:203], v[50:65]
	v_exp_f32_e32 v237, v81
	s_waitcnt vmcnt(0)
	s_add_u32 s4, s4, 0x180000
	s_addc_u32 s5, s5, 0
	s_add_i32 s16, s16, 2
	s_and_b64 vcc, exec, s[0:1]
	s_waitcnt vmcnt(0)
	s_barrier
	s_cbranch_vccnz .LBB0_911
.LBB0_907:
	s_add_i32 s0, s16, -1
	s_cmp_ge_u32 s0, s11
	s_nop 0
	s_cbranch_scc1 .LBB0_909
	s_add_u32 s0, s4, 0x15bc1800
	s_addc_u32 s1, s5, 0
	s_mov_b32 m0, s34
	s_nop 0
	global_load_lds_dwordx4 v170, s[0:1]
.LBB0_909:
	s_add_u32 s98, s4, s8
	s_addc_u32 s99, s5, s9
	s_mov_b32 m0, s30
	s_nop 0
	global_load_lds_dwordx4 v172, s[98:99]
	s_mov_b32 m0, s33
	s_nop 0
	global_load_lds_dwordx4 v174, s[98:99]
	ds_read_b128 v[96:99], v188 offset:32768
	ds_read_b128 v[100:103], v188 offset:36864
	ds_read_b128 v[192:195], v189 offset:32768
	ds_read_b128 v[196:199], v189 offset:36864
	ds_read_b128 v[200:203], v190 offset:32768
	ds_read_b128 v[204:207], v190 offset:36864
	ds_read_b128 v[208:211], v191 offset:32768
	ds_read_b128 v[212:215], v191 offset:36864
	s_waitcnt lgkmcnt(0)
	v_mfma_f32_32x32x16_bf16 v[112:127], v[96:99], v[128:131], 0
	v_mfma_f32_32x32x16_bf16 v[96:111], v[100:103], v[128:131], 0
	v_mfma_f32_32x32x16_bf16 v[112:127], v[192:195], v[132:135], v[112:127]
	v_mfma_f32_32x32x16_bf16 v[96:111], v[196:199], v[132:135], v[96:111]
	v_add_f32_e32 v67, v88, v1
	v_cvt_pk_bf16_f32 v66, v88, v1
	v_add_f32_e32 v1, v222, v223
	v_add_f32_e32 v67, v67, v82
	v_mfma_f32_32x32x16_bf16 v[112:127], v[200:203], v[136:139], v[112:127]
	v_add_f32_e32 v1, v1, v224
	v_add_f32_e32 v67, v67, v83
	v_cvt_pk_bf16_f32 v68, v84, v85
	v_add_f32_e32 v1, v1, v225
	v_add_f32_e32 v67, v67, v84
	v_cvt_pk_bf16_f32 v69, v86, v87
	v_add_f32_e32 v1, v1, v226
	v_add_f32_e32 v67, v67, v85
	v_mfma_f32_32x32x16_bf16 v[96:111], v[204:207], v[136:139], v[96:111]
	v_add_f32_e32 v1, v1, v227
	v_add_f32_e32 v67, v67, v86
	v_add_f32_e32 v1, v1, v228
	v_add_f32_e32 v67, v67, v87
	v_add_f32_e32 v1, v1, v229
	v_add_f32_e32 v67, v67, v90
	v_add_f32_e32 v1, v1, v230
	v_add_f32_e32 v67, v67, v89
	v_add_f32_e32 v1, v1, v231
	v_add_f32_e32 v67, v67, v92
	v_add_f32_e32 v1, v1, v232
	v_add_f32_e32 v67, v67, v91
	v_add_f32_e32 v1, v1, v233
	v_add_f32_e32 v67, v67, v94
	v_add_f32_e32 v1, v1, v234
	v_add_f32_e32 v67, v67, v93
	v_add_f32_e32 v1, v1, v235
	v_add_f32_e32 v67, v67, v95
	v_add_f32_e32 v1, v1, v236
	v_add_f32_e32 v67, v67, v151
	v_add_f32_e32 v1, v1, v237
	v_add_f32_e32 v1, v67, v1
	v_cvt_pk_bf16_f32 v67, v82, v83
	v_mfma_f32_32x32x16_bf16 v[112:127], v[208:211], v[140:143], v[112:127]
	v_cvt_pk_bf16_f32 v72, v90, v89
	v_cvt_pk_bf16_f32 v73, v92, v91
	v_cvt_pk_bf16_f32 v74, v94, v93
	v_cvt_pk_bf16_f32 v75, v95, v151
	v_cvt_pk_bf16_f32 v76, v222, v223
	v_cvt_pk_bf16_f32 v77, v224, v225
	v_cvt_pk_bf16_f32 v78, v226, v227
	v_mfma_f32_32x32x16_bf16 v[96:111], v[212:215], v[140:143], v[96:111]
	v_cvt_pk_bf16_f32 v79, v228, v229
	v_cvt_pk_bf16_f32 v80, v230, v231
	v_cvt_pk_bf16_f32 v81, v232, v233
	v_cvt_pk_bf16_f32 v82, v234, v235
	v_cvt_pk_bf16_f32 v83, v236, v237
	ds_read_b64_tr_b16 v[84:85], v185 offset:0
	ds_read_b64_tr_b16 v[86:87], v185 offset:0x800
	ds_read_b64_tr_b16 v[88:89], v185 offset:0x1000
	ds_read_b64_tr_b16 v[90:91], v185 offset:0x1800
	ds_read_b64_tr_b16 v[92:93], v185 offset:0x2000
	ds_read_b64_tr_b16 v[94:95], v185 offset:0x2800
	ds_read_b64_tr_b16 v[192:193], v185 offset:0x3000
	ds_read_b64_tr_b16 v[194:195], v185 offset:0x3800
	ds_read_b64_tr_b16 v[196:197], v185 offset:0x200
	ds_read_b64_tr_b16 v[198:199], v185 offset:0xa00
	ds_read_b64_tr_b16 v[200:201], v185 offset:0x1200
	ds_read_b64_tr_b16 v[202:203], v185 offset:0x1a00
	ds_read_b64_tr_b16 v[204:205], v185 offset:0x2200
	ds_read_b64_tr_b16 v[206:207], v185 offset:0x2a00
	ds_read_b64_tr_b16 v[208:209], v185 offset:0x3200
	ds_read_b64_tr_b16 v[210:211], v185 offset:0x3a00
	s_waitcnt lgkmcnt(8)
	s_nop 0
	v_mfma_f32_32x32x16_bf16 v[2:17], v[66:69], v[84:87], v[2:17]
	v_exp_f32_e32 v238, v112
	v_exp_f32_e32 v239, v113
	v_mfma_f32_32x32x16_bf16 v[2:17], v[72:75], v[88:91], v[2:17]
	v_exp_f32_e32 v240, v114
	v_exp_f32_e32 v241, v115
	v_mfma_f32_32x32x16_bf16 v[2:17], v[76:79], v[92:95], v[2:17]
	v_exp_f32_e32 v244, v116
	v_exp_f32_e32 v245, v117
	v_mfma_f32_32x32x16_bf16 v[2:17], v[80:83], v[192:195], v[2:17]
	v_exp_f32_e32 v246, v118
	v_exp_f32_e32 v247, v119
	ds_read_b64_tr_b16 v[84:85], v185 offset:0x400
	ds_read_b64_tr_b16 v[86:87], v185 offset:0xc00
	ds_read_b64_tr_b16 v[88:89], v185 offset:0x1400
	ds_read_b64_tr_b16 v[90:91], v185 offset:0x1c00
	ds_read_b64_tr_b16 v[92:93], v185 offset:0x2400
	ds_read_b64_tr_b16 v[94:95], v185 offset:0x2c00
	ds_read_b64_tr_b16 v[192:193], v185 offset:0x3400
	ds_read_b64_tr_b16 v[194:195], v185 offset:0x3c00
	s_waitcnt lgkmcnt(8)
	v_mfma_f32_32x32x16_bf16 v[18:33], v[66:69], v[196:199], v[18:33]
	v_exp_f32_e32 v248, v120
	v_exp_f32_e32 v249, v121
	v_mfma_f32_32x32x16_bf16 v[18:33], v[72:75], v[200:203], v[18:33]
	v_exp_f32_e32 v250, v122
	v_exp_f32_e32 v251, v123
	v_mfma_f32_32x32x16_bf16 v[18:33], v[76:79], v[204:207], v[18:33]
	v_exp_f32_e32 v252, v124
	v_exp_f32_e32 v253, v125
	v_mfma_f32_32x32x16_bf16 v[18:33], v[80:83], v[208:211], v[18:33]
	v_exp_f32_e32 v254, v126
	v_exp_f32_e32 v255, v127
	ds_read_b64_tr_b16 v[196:197], v185 offset:0x600
	ds_read_b64_tr_b16 v[198:199], v185 offset:0xe00
	ds_read_b64_tr_b16 v[200:201], v185 offset:0x1600
	ds_read_b64_tr_b16 v[202:203], v185 offset:0x1e00
	ds_read_b64_tr_b16 v[204:205], v185 offset:0x2600
	ds_read_b64_tr_b16 v[206:207], v185 offset:0x2e00
	ds_read_b64_tr_b16 v[208:209], v185 offset:0x3600
	ds_read_b64_tr_b16 v[210:211], v185 offset:0x3e00
	s_waitcnt lgkmcnt(8)
	v_mfma_f32_32x32x16_bf16 v[34:49], v[66:69], v[84:87], v[34:49]
	v_exp_f32_e32 v222, v96
	v_exp_f32_e32 v223, v97
	v_mfma_f32_32x32x16_bf16 v[34:49], v[72:75], v[88:91], v[34:49]
	v_exp_f32_e32 v224, v98
	v_exp_f32_e32 v225, v99
	v_mfma_f32_32x32x16_bf16 v[34:49], v[76:79], v[92:95], v[34:49]
	v_exp_f32_e32 v226, v100
	v_exp_f32_e32 v227, v101
	v_mfma_f32_32x32x16_bf16 v[34:49], v[80:83], v[192:195], v[34:49]
	v_exp_f32_e32 v228, v102
	v_exp_f32_e32 v229, v103
	s_waitcnt lgkmcnt(0)
	v_mfma_f32_32x32x16_bf16 v[50:65], v[66:69], v[196:199], v[50:65]
	v_exp_f32_e32 v230, v104
	v_exp_f32_e32 v231, v105
	v_mfma_f32_32x32x16_bf16 v[50:65], v[72:75], v[200:203], v[50:65]
	v_exp_f32_e32 v232, v106
	v_exp_f32_e32 v233, v107
	v_mfma_f32_32x32x16_bf16 v[50:65], v[76:79], v[204:207], v[50:65]
	v_exp_f32_e32 v234, v108
	v_exp_f32_e32 v235, v109
	v_mfma_f32_32x32x16_bf16 v[50:65], v[80:83], v[208:211], v[50:65]
	v_exp_f32_e32 v236, v110
	v_exp_f32_e32 v237, v111
	s_waitcnt vmcnt(0)
	s_cmp_ge_u32 s16, s11
	s_cselect_b64 s[0:1], -1, 0
	s_and_b64 vcc, exec, s[0:1]
	s_waitcnt vmcnt(0)
	s_barrier
	s_cbranch_vccnz .LBB0_906
	s_add_u32 s18, s4, 0x15c81800
	s_addc_u32 s19, s5, 0
	s_mov_b32 m0, s31
	s_nop 0
	global_load_lds_dwordx4 v170, s[18:19]
	s_branch .LBB0_906

.LBB0_2319:
	s_add_u32 s100, s0, s44
	s_addc_u32 s101, s1, s45
	s_mov_b32 m0, s56
	s_nop 0
	global_load_lds_dwordx4 v152, s[100:101]
	s_mov_b32 m0, s57
	s_nop 0
	global_load_lds_dwordx4 v154, s[100:101]
	ds_read_b128 v[68:71], v172 offset:40960
	ds_read_b128 v[72:75], v172 offset:45056
	ds_read_b128 v[156:159], v173 offset:40960
	ds_read_b128 v[176:179], v173 offset:45056
	ds_read_b128 v[180:183], v174 offset:40960
	ds_read_b128 v[184:187], v174 offset:45056
	ds_read_b128 v[188:191], v175 offset:40960
	ds_read_b128 v[192:195], v175 offset:45056
	v_add_f32_e32 v219, v219, v66
	s_add_i32 s52, s52, 2
	s_waitcnt lgkmcnt(0)
	v_mfma_f32_32x32x16_bf16 v[98:113], v[68:71], v[114:117], 0
	v_mfma_f32_32x32x16_bf16 v[66:81], v[72:75], v[114:117], 0
	v_mfma_f32_32x32x16_bf16 v[66:81], v[176:179], v[118:121], v[66:81]
	v_mfma_f32_32x32x16_bf16 v[98:113], v[156:159], v[118:121], v[98:113]
	v_add_f32_e32 v82, v236, v237
	v_add_f32_e32 v83, v220, v221
	v_mfma_f32_32x32x16_bf16 v[66:81], v[184:187], v[122:125], v[66:81]
	v_add_f32_e32 v82, v82, v238
	v_add_f32_e32 v83, v83, v222
	v_cvt_pk_bf16_f32 v84, v240, v241
	v_add_f32_e32 v82, v82, v239
	v_add_f32_e32 v83, v83, v223
	v_cvt_pk_bf16_f32 v85, v244, v245
	v_add_f32_e32 v82, v82, v240
	v_add_f32_e32 v83, v83, v224
	v_mfma_f32_32x32x16_bf16 v[98:113], v[180:183], v[122:125], v[98:113]
	v_add_f32_e32 v82, v82, v241
	v_add_f32_e32 v83, v83, v225
	v_add_f32_e32 v82, v82, v244
	v_add_f32_e32 v83, v83, v226
	v_add_f32_e32 v82, v82, v245
	v_add_f32_e32 v83, v83, v227
	v_add_f32_e32 v82, v82, v246
	v_add_f32_e32 v83, v83, v228
	v_add_f32_e32 v82, v82, v247
	v_add_f32_e32 v83, v83, v229
	v_add_f32_e32 v82, v82, v248
	v_add_f32_e32 v83, v83, v230
	v_add_f32_e32 v82, v82, v249
	v_add_f32_e32 v83, v83, v231
	v_add_f32_e32 v82, v82, v250
	v_add_f32_e32 v83, v83, v232
	v_add_f32_e32 v82, v82, v251
	v_add_f32_e32 v83, v83, v233
	v_add_f32_e32 v82, v82, v252
	v_add_f32_e32 v83, v83, v234
	v_add_f32_e32 v82, v82, v253
	v_add_f32_e32 v83, v83, v235
	v_add_f32_e32 v82, v82, v83
	v_add_f32_e32 v219, v219, v82
	v_cvt_pk_bf16_f32 v82, v236, v237
	v_cvt_pk_bf16_f32 v83, v238, v239
	v_mfma_f32_32x32x16_bf16 v[66:81], v[192:195], v[126:129], v[66:81]
	v_cvt_pk_bf16_f32 v86, v246, v247
	v_cvt_pk_bf16_f32 v87, v248, v249
	v_cvt_pk_bf16_f32 v88, v250, v251
	v_cvt_pk_bf16_f32 v89, v252, v253
	v_cvt_pk_bf16_f32 v90, v220, v221
	v_cvt_pk_bf16_f32 v91, v222, v223
	v_cvt_pk_bf16_f32 v92, v224, v225
	v_cvt_pk_bf16_f32 v93, v226, v227
	v_cvt_pk_bf16_f32 v94, v228, v229
	v_cvt_pk_bf16_f32 v95, v230, v231
	v_cvt_pk_bf16_f32 v96, v232, v233
	v_cvt_pk_bf16_f32 v97, v234, v235
	v_mfma_f32_32x32x16_bf16 v[98:113], v[188:191], v[126:129], v[98:113]
	ds_read_b64_tr_b16 v[156:157], v168 offset:0
	ds_read_b64_tr_b16 v[158:159], v168 offset:0x800
	ds_read_b64_tr_b16 v[176:177], v168 offset:0x1000
	ds_read_b64_tr_b16 v[178:179], v168 offset:0x1800
	ds_read_b64_tr_b16 v[180:181], v168 offset:0x2000
	ds_read_b64_tr_b16 v[182:183], v168 offset:0x2800
	ds_read_b64_tr_b16 v[184:185], v168 offset:0x3000
	ds_read_b64_tr_b16 v[186:187], v168 offset:0x3800
	ds_read_b64_tr_b16 v[188:189], v168 offset:0x200
	ds_read_b64_tr_b16 v[190:191], v168 offset:0xa00
	ds_read_b64_tr_b16 v[192:193], v168 offset:0x1200
	ds_read_b64_tr_b16 v[194:195], v168 offset:0x1a00
	ds_read_b64_tr_b16 v[196:197], v168 offset:0x2200
	ds_read_b64_tr_b16 v[198:199], v168 offset:0x2a00
	ds_read_b64_tr_b16 v[200:201], v168 offset:0x3200
	ds_read_b64_tr_b16 v[202:203], v168 offset:0x3a00
	s_waitcnt lgkmcnt(8)
	s_nop 0
	v_mfma_f32_32x32x16_bf16 v[2:17], v[82:85], v[156:159], v[2:17]
	v_exp_f32_e32 v220, v66
	s_nop 3
	v_exp_f32_e32 v139, v98
	v_exp_f32_e32 v141, v99
	v_exp_f32_e32 v143, v100
	v_exp_f32_e32 v145, v101
	v_mfma_f32_32x32x16_bf16 v[2:17], v[86:89], v[176:179], v[2:17]
	v_exp_f32_e32 v221, v67
	v_mfma_f32_32x32x16_bf16 v[2:17], v[90:93], v[180:183], v[2:17]
	v_exp_f32_e32 v222, v68
	v_mfma_f32_32x32x16_bf16 v[2:17], v[94:97], v[184:187], v[2:17]
	v_exp_f32_e32 v223, v69
	ds_read_b64_tr_b16 v[98:99], v168 offset:0x400
	ds_read_b64_tr_b16 v[100:101], v168 offset:0xc00
	ds_read_b64_tr_b16 v[156:157], v168 offset:0x1400
	ds_read_b64_tr_b16 v[158:159], v168 offset:0x1c00
	ds_read_b64_tr_b16 v[178:179], v168 offset:0x2400
	ds_read_b64_tr_b16 v[180:181], v168 offset:0x2c00
	ds_read_b64_tr_b16 v[182:183], v168 offset:0x3400
	ds_read_b64_tr_b16 v[184:185], v168 offset:0x3c00
	s_waitcnt lgkmcnt(8)
	v_mfma_f32_32x32x16_bf16 v[18:33], v[82:85], v[188:191], v[18:33]
	v_exp_f32_e32 v224, v70
	v_exp_f32_e32 v147, v102
	v_exp_f32_e32 v149, v103
	v_exp_f32_e32 v176, v104
	v_exp_f32_e32 v177, v105
	v_mfma_f32_32x32x16_bf16 v[18:33], v[86:89], v[192:195], v[18:33]
	v_exp_f32_e32 v225, v71
	v_mfma_f32_32x32x16_bf16 v[18:33], v[90:93], v[196:199], v[18:33]
	v_exp_f32_e32 v226, v72
	v_mfma_f32_32x32x16_bf16 v[18:33], v[94:97], v[200:203], v[18:33]
	v_exp_f32_e32 v227, v73
	ds_read_b64_tr_b16 v[102:103], v168 offset:0x600
	ds_read_b64_tr_b16 v[104:105], v168 offset:0xe00
	ds_read_b64_tr_b16 v[186:187], v168 offset:0x1600
	ds_read_b64_tr_b16 v[188:189], v168 offset:0x1e00
	ds_read_b64_tr_b16 v[190:191], v168 offset:0x2600
	ds_read_b64_tr_b16 v[192:193], v168 offset:0x2e00
	ds_read_b64_tr_b16 v[194:195], v168 offset:0x3600
	ds_read_b64_tr_b16 v[196:197], v168 offset:0x3e00
	s_waitcnt lgkmcnt(8)
	v_mfma_f32_32x32x16_bf16 v[34:49], v[82:85], v[98:101], v[34:49]
	v_exp_f32_e32 v228, v74
	v_mfma_f32_32x32x16_bf16 v[34:49], v[86:89], v[156:159], v[34:49]
	v_exp_f32_e32 v229, v75
	v_mfma_f32_32x32x16_bf16 v[34:49], v[90:93], v[178:181], v[34:49]
	v_exp_f32_e32 v230, v76
	v_exp_f32_e32 v178, v106
	v_exp_f32_e32 v179, v107
	v_exp_f32_e32 v180, v108
	v_exp_f32_e32 v181, v109
	v_mfma_f32_32x32x16_bf16 v[34:49], v[94:97], v[182:185], v[34:49]
	v_exp_f32_e32 v231, v77
	s_waitcnt lgkmcnt(0)
	v_mfma_f32_32x32x16_bf16 v[50:65], v[82:85], v[102:105], v[50:65]
	v_exp_f32_e32 v232, v78
	v_exp_f32_e32 v182, v110
	v_exp_f32_e32 v183, v111
	v_exp_f32_e32 v184, v112
	v_exp_f32_e32 v185, v113
	v_mfma_f32_32x32x16_bf16 v[50:65], v[86:89], v[186:189], v[50:65]
	v_exp_f32_e32 v233, v79
	v_mfma_f32_32x32x16_bf16 v[50:65], v[90:93], v[190:193], v[50:65]
	v_exp_f32_e32 v234, v80
	v_mfma_f32_32x32x16_bf16 v[50:65], v[94:97], v[194:197], v[50:65]
	v_exp_f32_e32 v235, v81
	s_waitcnt vmcnt(0)
	s_add_u32 s0, s0, 0x180000
	s_addc_u32 s1, s1, 0
	s_and_b64 vcc, exec, s[24:25]
	s_waitcnt vmcnt(0)
	s_barrier
	s_cbranch_vccnz .LBB0_2322
.LBB0_2320:
	v_lshl_add_u64 v[160:161], s[0:1], 0, v[150:151]
	s_mov_b32 m0, s55
	v_lshl_add_u64 v[82:83], v[160:161], 0, s[18:19]
	s_add_u32 s98, s0, s36
	global_load_lds_dwordx4 v[82:83], off
	s_addc_u32 s99, s1, s37
	s_mov_b32 m0, s34
	s_nop 0
	global_load_lds_dwordx4 v152, s[98:99]
	s_mov_b32 m0, s54
	s_nop 0
	global_load_lds_dwordx4 v154, s[98:99]
	ds_read_b128 v[82:85], v172 offset:32768
	ds_read_b128 v[86:89], v172 offset:36864
	ds_read_b128 v[186:189], v173 offset:32768
	ds_read_b128 v[190:193], v173 offset:36864
	ds_read_b128 v[194:197], v174 offset:32768
	ds_read_b128 v[198:201], v174 offset:36864
	ds_read_b128 v[202:205], v175 offset:32768
	ds_read_b128 v[206:209], v175 offset:36864
	s_waitcnt lgkmcnt(0)
	v_mfma_f32_32x32x16_bf16 v[98:113], v[82:85], v[114:117], 0
	v_mfma_f32_32x32x16_bf16 v[82:97], v[86:89], v[114:117], 0
	v_mfma_f32_32x32x16_bf16 v[98:113], v[186:189], v[118:121], v[98:113]
	v_mfma_f32_32x32x16_bf16 v[82:97], v[190:193], v[118:121], v[82:97]
	v_add_f32_e32 v66, v139, v141
	v_add_f32_e32 v67, v220, v221
	v_mfma_f32_32x32x16_bf16 v[98:113], v[194:197], v[122:125], v[98:113]
	v_add_f32_e32 v66, v66, v143
	v_add_f32_e32 v67, v67, v222
	v_cvt_pk_bf16_f32 v68, v139, v141
	v_add_f32_e32 v66, v66, v145
	v_add_f32_e32 v67, v67, v223
	v_cvt_pk_bf16_f32 v69, v143, v145
	v_add_f32_e32 v66, v66, v147
	v_add_f32_e32 v67, v67, v224
	v_mfma_f32_32x32x16_bf16 v[82:97], v[198:201], v[122:125], v[82:97]
	v_add_f32_e32 v66, v66, v149
	v_add_f32_e32 v67, v67, v225
	v_cvt_pk_bf16_f32 v70, v147, v149
	v_add_f32_e32 v66, v66, v176
	v_add_f32_e32 v67, v67, v226
	v_cvt_pk_bf16_f32 v71, v176, v177
	v_add_f32_e32 v66, v66, v177
	v_add_f32_e32 v67, v67, v227
	s_nop 0
	v_add_f32_e32 v66, v66, v178
	v_add_f32_e32 v67, v67, v228
	v_add_f32_e32 v66, v66, v179
	v_add_f32_e32 v67, v67, v229
	v_add_f32_e32 v66, v66, v180
	v_add_f32_e32 v67, v67, v230
	v_add_f32_e32 v66, v66, v181
	v_add_f32_e32 v67, v67, v231
	v_add_f32_e32 v66, v66, v182
	v_add_f32_e32 v67, v67, v232
	v_add_f32_e32 v66, v66, v183
	v_add_f32_e32 v67, v67, v233
	v_add_f32_e32 v66, v66, v184
	v_add_f32_e32 v67, v67, v234
	v_add_f32_e32 v66, v66, v185
	v_add_f32_e32 v67, v67, v235
	v_add_f32_e32 v66, v66, v67
	v_mfma_f32_32x32x16_bf16 v[98:113], v[202:205], v[126:129], v[98:113]
	v_cvt_pk_bf16_f32 v72, v178, v179
	v_cvt_pk_bf16_f32 v73, v180, v181
	v_cvt_pk_bf16_f32 v74, v182, v183
	v_cvt_pk_bf16_f32 v75, v184, v185
	v_cvt_pk_bf16_f32 v76, v220, v221
	v_cvt_pk_bf16_f32 v77, v222, v223
	v_cvt_pk_bf16_f32 v78, v224, v225
	v_mfma_f32_32x32x16_bf16 v[82:97], v[206:209], v[126:129], v[82:97]
	v_cvt_pk_bf16_f32 v79, v226, v227
	v_cvt_pk_bf16_f32 v176, v228, v229
	v_cvt_pk_bf16_f32 v177, v230, v231
	v_cvt_pk_bf16_f32 v178, v232, v233
	v_cvt_pk_bf16_f32 v179, v234, v235
	ds_read_b64_tr_b16 v[180:181], v169 offset:0
	ds_read_b64_tr_b16 v[182:183], v169 offset:0x800
	ds_read_b64_tr_b16 v[184:185], v169 offset:0x1000
	ds_read_b64_tr_b16 v[186:187], v169 offset:0x1800
	ds_read_b64_tr_b16 v[188:189], v169 offset:0x2000
	ds_read_b64_tr_b16 v[190:191], v169 offset:0x2800
	ds_read_b64_tr_b16 v[192:193], v169 offset:0x3000
	ds_read_b64_tr_b16 v[194:195], v169 offset:0x3800
	ds_read_b64_tr_b16 v[196:197], v169 offset:0x200
	ds_read_b64_tr_b16 v[198:199], v169 offset:0xa00
	ds_read_b64_tr_b16 v[200:201], v169 offset:0x1200
	ds_read_b64_tr_b16 v[202:203], v169 offset:0x1a00
	ds_read_b64_tr_b16 v[204:205], v169 offset:0x2200
	ds_read_b64_tr_b16 v[206:207], v169 offset:0x2a00
	ds_read_b64_tr_b16 v[208:209], v169 offset:0x3200
	ds_read_b64_tr_b16 v[210:211], v169 offset:0x3a00
	s_waitcnt lgkmcnt(8)
	s_nop 0
	v_mfma_f32_32x32x16_bf16 v[2:17], v[68:71], v[180:183], v[2:17]
	v_exp_f32_e32 v236, v98
	v_exp_f32_e32 v237, v99
	v_mfma_f32_32x32x16_bf16 v[2:17], v[72:75], v[184:187], v[2:17]
	v_exp_f32_e32 v238, v100
	v_exp_f32_e32 v239, v101
	v_mfma_f32_32x32x16_bf16 v[2:17], v[76:79], v[188:191], v[2:17]
	v_exp_f32_e32 v240, v102
	v_exp_f32_e32 v241, v103
	v_mfma_f32_32x32x16_bf16 v[2:17], v[176:179], v[192:195], v[2:17]
	v_exp_f32_e32 v244, v104
	v_exp_f32_e32 v245, v105
	ds_read_b64_tr_b16 v[180:181], v169 offset:0x400
	ds_read_b64_tr_b16 v[182:183], v169 offset:0xc00
	ds_read_b64_tr_b16 v[184:185], v169 offset:0x1400
	ds_read_b64_tr_b16 v[186:187], v169 offset:0x1c00
	ds_read_b64_tr_b16 v[188:189], v169 offset:0x2400
	ds_read_b64_tr_b16 v[190:191], v169 offset:0x2c00
	ds_read_b64_tr_b16 v[192:193], v169 offset:0x3400
	ds_read_b64_tr_b16 v[194:195], v169 offset:0x3c00
	s_waitcnt lgkmcnt(8)
	v_mfma_f32_32x32x16_bf16 v[18:33], v[68:71], v[196:199], v[18:33]
	v_exp_f32_e32 v246, v106
	v_exp_f32_e32 v247, v107
	v_mfma_f32_32x32x16_bf16 v[18:33], v[72:75], v[200:203], v[18:33]
	v_exp_f32_e32 v248, v108
	v_exp_f32_e32 v249, v109
	v_mfma_f32_32x32x16_bf16 v[18:33], v[76:79], v[204:207], v[18:33]
	v_exp_f32_e32 v250, v110
	v_exp_f32_e32 v251, v111
	v_mfma_f32_32x32x16_bf16 v[18:33], v[176:179], v[208:211], v[18:33]
	v_exp_f32_e32 v252, v112
	v_exp_f32_e32 v253, v113
	ds_read_b64_tr_b16 v[196:197], v169 offset:0x600
	ds_read_b64_tr_b16 v[198:199], v169 offset:0xe00
	ds_read_b64_tr_b16 v[200:201], v169 offset:0x1600
	ds_read_b64_tr_b16 v[202:203], v169 offset:0x1e00
	ds_read_b64_tr_b16 v[204:205], v169 offset:0x2600
	ds_read_b64_tr_b16 v[206:207], v169 offset:0x2e00
	ds_read_b64_tr_b16 v[208:209], v169 offset:0x3600
	ds_read_b64_tr_b16 v[210:211], v169 offset:0x3e00
	s_waitcnt lgkmcnt(8)
	v_mfma_f32_32x32x16_bf16 v[34:49], v[68:71], v[180:183], v[34:49]
	v_exp_f32_e32 v220, v82
	v_exp_f32_e32 v221, v83
	v_mfma_f32_32x32x16_bf16 v[34:49], v[72:75], v[184:187], v[34:49]
	v_exp_f32_e32 v222, v84
	v_exp_f32_e32 v223, v85
	v_mfma_f32_32x32x16_bf16 v[34:49], v[76:79], v[188:191], v[34:49]
	v_exp_f32_e32 v224, v86
	v_exp_f32_e32 v225, v87
	v_mfma_f32_32x32x16_bf16 v[34:49], v[176:179], v[192:195], v[34:49]
	v_exp_f32_e32 v226, v88
	v_exp_f32_e32 v227, v89
	s_waitcnt lgkmcnt(0)
	v_mfma_f32_32x32x16_bf16 v[50:65], v[68:71], v[196:199], v[50:65]
	v_exp_f32_e32 v228, v90
	v_exp_f32_e32 v229, v91
	v_mfma_f32_32x32x16_bf16 v[50:65], v[72:75], v[200:203], v[50:65]
	v_exp_f32_e32 v230, v92
	v_exp_f32_e32 v231, v93
	v_mfma_f32_32x32x16_bf16 v[50:65], v[76:79], v[204:207], v[50:65]
	v_exp_f32_e32 v232, v94
	v_exp_f32_e32 v233, v95
	v_mfma_f32_32x32x16_bf16 v[50:65], v[176:179], v[208:211], v[50:65]
	v_exp_f32_e32 v234, v96
	v_exp_f32_e32 v235, v97
	s_waitcnt vmcnt(0)
	s_cmpk_gt_u32 s52, 0x101
	s_cselect_b64 s[24:25], -1, 0
	s_and_b64 vcc, exec, s[24:25]
	s_waitcnt vmcnt(0)
	s_barrier
	s_cbranch_vccnz .LBB0_2319
	v_lshl_add_u64 v[68:69], v[160:161], 0, s[38:39]
	s_mov_b32 m0, s35
	s_nop 0
	global_load_lds_dwordx4 v[68:69], off
	s_branch .LBB0_2319
